# attention loop: prefetch all 12 K fragments into free VGPRs up front; cross-half max via v_permlane32_swap instead of ds_bpermute
# speedup vs baseline: 1.0020x; 1.0020x over previous
; #define LAS __attribute__((address_space(3)))
; #define AT_GA(g) { bf16x8 na = ka; if ((g) < 5) na = *(const LAS bf16x8*)(Kb + ((g) + 1) * 32); else na = *(const LAS bf16x8*)(Kb + 32 * KT_STRIDE); \
;         if ((g) == 0) C0 = AT_MFMA(ka, qr[0], negm, 0, 0, 0); else C0 = AT_MFMA(ka, qr[g], C0, 0, 0, 0); ka = na; }
; #define AT_GA(g) { bf16x8 na = ka; if ((g) < 5) na = *(const LAS bf16x8*)(Kb + 32 * KT_STRIDE + ((g) + 1) * 32); \
;         if ((g) == 0) C1 = AT_MFMA(ka, qr[0], negm, 0, 0, 0); else C1 = AT_MFMA(ka, qr[g], C1, 0, 0, 0); ka = na; }
; template <bool FIRST>
; __device__ __forceinline__ void at_step(f32x16& o0, f32x16& o1, f32x16& negm, float& mrun, float& lrun, const bf16x8 (&qr)[6], const LAS unsigned char* Kb, const LAS unsigned char* Vb) {
;     f32x16 C0, C1;
;     {   bf16x8 ka = *(const LAS bf16x8*)(Kb);
;     ...
;         AT_GA(0) AT_GA(1) AT_GA(2) AT_GA(3) AT_GA(4) AT_GA(5)
;     ...
;         AT_GA(0) AT_GA(1) AT_GA(2) AT_GA(3) AT_GA(4) AT_GA(5)
;     ...
;     }
;     bf16x8 va = *(const LAS bf16x8*)(Vb), vb = *(const LAS bf16x8*)(Vb + 32 * VT_STRIDE);
;     float sacc = 0.f;
;     ...
;     {   float rm = fmaxf(fmaxf(C0[0], C0[1]), C0[2]);
; #pragma unroll
;         for (int r = 3; r < 15; r += 2) rm = fmaxf(fmaxf(rm, C0[r]), C0[r + 1]);
;         rm = fmaxf(rm, C0[15]);
;         rm = fmaxf(rm, __shfl_xor(rm, 32));
;         if (FIRST) { const float dl = rm; mrun = dl;
; #pragma unroll
;             for (int r = 0; r < 16; ++r) { C0[r] -= dl; C1[r] -= dl; negm[r] = -mrun; }
;             asm volatile("" : "+v"(negm));
;         } else if (__builtin_expect(__any(rm > 8.f), 0)) { const float dl = fmaxf(rm, 0.f); mrun += dl;
; #pragma unroll
;             for (int r = 0; r < 16; ++r) { C0[r] -= dl; C1[r] -= dl; negm[r] = -mrun; }
;             asm volatile("" : "+v"(negm));
;             const float f = __builtin_amdgcn_exp2f(-dl); lrun *= f;
; #pragma unroll
;             for (int r = 0; r < 16; ++r) { o0[r] *= f; o1[r] *= f; } }
;     }
;     AT_GB(0, C0, 0) AT_GB(1, C0, 8)
;     lrun += sacc; sacc = 0.f;
;     {   float rm = fmaxf(fmaxf(C1[0], C1[1]), C1[2]);
; #pragma unroll
;         for (int r = 3; r < 15; r += 2) rm = fmaxf(fmaxf(rm, C1[r]), C1[r + 1]);
;         rm = fmaxf(rm, C1[15]);
;         rm = fmaxf(rm, __shfl_xor(rm, 32));
;         if (__builtin_expect(__any(rm > 8.f), 0)) { const float dl = fmaxf(rm, 0.f); mrun += dl;
.LBB0_1188:
	ds_read_b128 v[178:181], v156 offset:13312
	ds_read_b128 v[182:185], v156 offset:13344
	ds_read_b128 v[186:189], v156 offset:13376
	ds_read_b128 v[190:193], v156 offset:13408
	ds_read_b128 v[194:197], v156 offset:13440
	ds_read_b128 v[198:201], v156 offset:13472
	ds_read_b128 v[202:205], v156 offset:19968
	ds_read_b128 v[206:209], v156 offset:20000
	ds_read_b128 v[210:213], v156 offset:20032
	ds_read_b128 v[214:217], v156 offset:20064
	ds_read_b128 v[218:221], v156 offset:20096
	ds_read_b128 v[222:225], v156 offset:20128
	s_waitcnt lgkmcnt(11)
	v_mfma_f32_32x32x16_bf16 v[68:83], v[178:181], v[104:107], v[36:51]
	s_waitcnt lgkmcnt(10)
	v_mfma_f32_32x32x16_bf16 v[68:83], v[182:185], v[100:103], v[68:83]
	s_waitcnt lgkmcnt(9)
	v_mfma_f32_32x32x16_bf16 v[68:83], v[186:189], v[96:99], v[68:83]
	s_waitcnt lgkmcnt(8)
	v_mfma_f32_32x32x16_bf16 v[68:83], v[190:193], v[92:95], v[68:83]
	s_waitcnt lgkmcnt(7)
	v_mfma_f32_32x32x16_bf16 v[68:83], v[194:197], v[88:91], v[68:83]
	s_waitcnt lgkmcnt(6)
	v_mfma_f32_32x32x16_bf16 v[68:83], v[198:201], v[84:87], v[68:83]
	ds_read_b128 v[136:139], v154 offset:35840
	ds_read_b128 v[132:135], v154 offset:40448
	s_waitcnt lgkmcnt(7)
	v_mfma_f32_32x32x16_bf16 v[52:67], v[202:205], v[104:107], v[36:51]
	s_waitcnt lgkmcnt(6)
	v_mfma_f32_32x32x16_bf16 v[52:67], v[206:209], v[100:103], v[52:67]
	s_waitcnt lgkmcnt(5)
	v_mfma_f32_32x32x16_bf16 v[52:67], v[210:213], v[96:99], v[52:67]
	s_waitcnt lgkmcnt(4)
	v_mfma_f32_32x32x16_bf16 v[52:67], v[214:217], v[92:95], v[52:67]
	s_nop 1
	v_max3_f32 v226, v68, v69, v70
	v_max3_f32 v226, v226, v71, v72
	v_max3_f32 v226, v226, v73, v74
	v_max3_f32 v226, v226, v75, v76
	v_max3_f32 v226, v226, v77, v78
	v_max3_f32 v226, v226, v79, v80
	v_max3_f32 v226, v226, v81, v82
	v_max_f32_e32 v158, v226, v83
	v_mov_b32_e32 v159, v158
	s_waitcnt lgkmcnt(3)
	v_mfma_f32_32x32x16_bf16 v[52:67], v[218:221], v[88:91], v[52:67]
	v_permlane32_swap_b32_e32 v158, v159
	s_waitcnt lgkmcnt(2)
	v_mfma_f32_32x32x16_bf16 v[52:67], v[222:225], v[84:87], v[52:67]
	v_max_f32_e32 v163, v158, v159
	v_cmp_lt_f32_e32 vcc, s70, v163
	s_cbranch_vccnz .LBB0_1202
.LBB0_1189:
	v_exp_f32_e32 v159, v68
	v_exp_f32_e32 v165, v69
	v_exp_f32_e32 v167, v70
	v_exp_f32_e32 v169, v71
	v_exp_f32_e32 v171, v72
	v_exp_f32_e32 v173, v73
	v_exp_f32_e32 v175, v74
	v_exp_f32_e32 v177, v75
	v_cvt_pk_bf16_f32 v68, v159, v165
	v_cvt_pk_bf16_f32 v69, v167, v169
	v_cvt_pk_bf16_f32 v70, v171, v173
	v_cvt_pk_bf16_f32 v71, v175, v177
	v_exp_f32_e32 v164, v82
	v_exp_f32_e32 v158, v83
	v_max_f32_e32 v82, v53, v53
	v_max_f32_e32 v83, v52, v52
	s_waitcnt lgkmcnt(1)
	v_mfma_f32_32x32x16_bf16 v[20:35], v[136:139], v[68:71], v[20:35]
	v_exp_f32_e32 v170, v76
	v_exp_f32_e32 v172, v77
	v_exp_f32_e32 v174, v78
	v_exp_f32_e32 v176, v79
	v_max_f32_e32 v82, v83, v82
	v_exp_f32_e32 v166, v80
	v_exp_f32_e32 v168, v81
	s_waitcnt lgkmcnt(0)
	v_mfma_f32_32x32x16_bf16 v[4:19], v[132:135], v[68:71], v[4:19]
	v_max3_f32 v82, v82, v54, v55
	v_max3_f32 v82, v82, v56, v57
	v_max3_f32 v82, v82, v58, v59
	ds_read_b128 v[132:135], v154 offset:35872
	ds_read_b128 v[72:75], v154 offset:35904
	ds_read_b128 v[136:139], v154 offset:40480
	ds_read_b128 v[68:71], v154 offset:40512
	v_pk_add_f32 v[76:77], v[172:173], v[170:171]
	v_pk_add_f32 v[78:79], v[176:177], v[174:175]
	v_max3_f32 v82, v82, v60, v61
	v_pk_add_f32 v[76:77], v[78:79], v[76:77]
	v_pk_add_f32 v[78:79], v[168:169], v[166:167]
	v_pk_add_f32 v[80:81], v[164:165], v[158:159]
	v_max3_f32 v82, v82, v62, v63
	v_pk_add_f32 v[78:79], v[78:79], v[80:81]
	v_max3_f32 v82, v82, v64, v65
	v_pk_add_f32 v[80:81], v[76:77], v[78:79]
	v_cvt_pk_bf16_f32 v76, v170, v172
	v_cvt_pk_bf16_f32 v77, v174, v176
	v_cvt_pk_bf16_f32 v78, v166, v168
	v_cvt_pk_bf16_f32 v79, v164, v158
	v_max3_f32 v82, v82, v66, v67
	v_mov_b32_e32 v83, v82
	s_waitcnt lgkmcnt(3)
	v_mfma_f32_32x32x16_bf16 v[20:35], v[132:135], v[76:79], v[20:35]
	v_add_f32_e32 v81, 0, v81
	v_add_f32_e32 v80, v80, v81
	v_permlane32_swap_b32_e32 v82, v83
	s_waitcnt lgkmcnt(1)
	v_mfma_f32_32x32x16_bf16 v[4:19], v[136:139], v[76:79], v[4:19]
	s_waitcnt lgkmcnt(0)
	v_max_f32_e32 v77, v82, v83
	v_add_f32_e32 v76, v162, v80
	v_cmp_lt_f32_e32 vcc, s70, v77
	s_cbranch_vccnz .LBB0_1203

; #define LAS __attribute__((address_space(3)))
; #define AT_GA(g) { bf16x8 na = ka; if ((g) < 5) na = *(const LAS bf16x8*)(Kb + ((g) + 1) * 32); else na = *(const LAS bf16x8*)(Kb + 32 * KT_STRIDE); \
;         if ((g) == 0) C0 = AT_MFMA(ka, qr[0], negm, 0, 0, 0); else C0 = AT_MFMA(ka, qr[g], C0, 0, 0, 0); ka = na; }
; #define AT_GA(g) { bf16x8 na = ka; if ((g) < 5) na = *(const LAS bf16x8*)(Kb + 32 * KT_STRIDE + ((g) + 1) * 32); \
;         if ((g) == 0) C1 = AT_MFMA(ka, qr[0], negm, 0, 0, 0); else C1 = AT_MFMA(ka, qr[g], C1, 0, 0, 0); ka = na; }
; template <bool FIRST>
; __device__ __forceinline__ void at_step(f32x16& o0, f32x16& o1, f32x16& negm, float& mrun, float& lrun, const bf16x8 (&qr)[6], const LAS unsigned char* Kb, const LAS unsigned char* Vb) {
;     f32x16 C0, C1;
;     {   bf16x8 ka = *(const LAS bf16x8*)(Kb);
;     ...
;         AT_GA(0) AT_GA(1) AT_GA(2) AT_GA(3) AT_GA(4) AT_GA(5)
;     ...
;         AT_GA(0) AT_GA(1) AT_GA(2) AT_GA(3) AT_GA(4) AT_GA(5)
;     ...
;     }
;     bf16x8 va = *(const LAS bf16x8*)(Vb), vb = *(const LAS bf16x8*)(Vb + 32 * VT_STRIDE);
;     float sacc = 0.f;
;     ...
;     {   float rm = fmaxf(fmaxf(C0[0], C0[1]), C0[2]);
; #pragma unroll
;         for (int r = 3; r < 15; r += 2) rm = fmaxf(fmaxf(rm, C0[r]), C0[r + 1]);
;         rm = fmaxf(rm, C0[15]);
;         rm = fmaxf(rm, __shfl_xor(rm, 32));
;         if (FIRST) { const float dl = rm; mrun = dl;
; #pragma unroll
;             for (int r = 0; r < 16; ++r) { C0[r] -= dl; C1[r] -= dl; negm[r] = -mrun; }
;             asm volatile("" : "+v"(negm));
;         } else if (__builtin_expect(__any(rm > 8.f), 0)) { const float dl = fmaxf(rm, 0.f); mrun += dl;
; #pragma unroll
;             for (int r = 0; r < 16; ++r) { C0[r] -= dl; C1[r] -= dl; negm[r] = -mrun; }
;             asm volatile("" : "+v"(negm));
;             const float f = __builtin_amdgcn_exp2f(-dl); lrun *= f;
; #pragma unroll
;             for (int r = 0; r < 16; ++r) { o0[r] *= f; o1[r] *= f; } }
;     }
;     AT_GB(0, C0, 0) AT_GB(1, C0, 8)
;     lrun += sacc; sacc = 0.f;
;     {   float rm = fmaxf(fmaxf(C1[0], C1[1]), C1[2]);
; #pragma unroll
;         for (int r = 3; r < 15; r += 2) rm = fmaxf(fmaxf(rm, C1[r]), C1[r + 1]);
;         rm = fmaxf(rm, C1[15]);
;         rm = fmaxf(rm, __shfl_xor(rm, 32));
;         if (__builtin_expect(__any(rm > 8.f), 0)) { const float dl = fmaxf(rm, 0.f); mrun += dl;
.LBB0_1194:
	ds_read_b128 v[178:181], v156
	ds_read_b128 v[182:185], v156 offset:32
	ds_read_b128 v[186:189], v156 offset:64
	ds_read_b128 v[190:193], v156 offset:96
	ds_read_b128 v[194:197], v156 offset:128
	ds_read_b128 v[198:201], v156 offset:160
	ds_read_b128 v[202:205], v156 offset:6656
	ds_read_b128 v[206:209], v156 offset:6688
	ds_read_b128 v[210:213], v156 offset:6720
	ds_read_b128 v[214:217], v156 offset:6752
	ds_read_b128 v[218:221], v156 offset:6784
	ds_read_b128 v[222:225], v156 offset:6816
	s_waitcnt lgkmcnt(11)
	v_mfma_f32_32x32x16_bf16 v[68:83], v[178:181], v[104:107], v[36:51]
	s_waitcnt lgkmcnt(10)
	v_mfma_f32_32x32x16_bf16 v[68:83], v[182:185], v[100:103], v[68:83]
	s_waitcnt lgkmcnt(9)
	v_mfma_f32_32x32x16_bf16 v[68:83], v[186:189], v[96:99], v[68:83]
	s_waitcnt lgkmcnt(8)
	v_mfma_f32_32x32x16_bf16 v[68:83], v[190:193], v[92:95], v[68:83]
	s_waitcnt lgkmcnt(7)
	v_mfma_f32_32x32x16_bf16 v[68:83], v[194:197], v[88:91], v[68:83]
	s_waitcnt lgkmcnt(6)
	v_mfma_f32_32x32x16_bf16 v[68:83], v[198:201], v[84:87], v[68:83]
	ds_read_b128 v[136:139], v154 offset:26624
	ds_read_b128 v[132:135], v154 offset:31232
	s_waitcnt lgkmcnt(7)
	v_mfma_f32_32x32x16_bf16 v[52:67], v[202:205], v[104:107], v[36:51]
	s_waitcnt lgkmcnt(6)
	v_mfma_f32_32x32x16_bf16 v[52:67], v[206:209], v[100:103], v[52:67]
	s_waitcnt lgkmcnt(5)
	v_mfma_f32_32x32x16_bf16 v[52:67], v[210:213], v[96:99], v[52:67]
	s_waitcnt lgkmcnt(4)
	v_mfma_f32_32x32x16_bf16 v[52:67], v[214:217], v[92:95], v[52:67]
	s_nop 1
	v_max3_f32 v226, v68, v69, v70
	v_max3_f32 v226, v226, v71, v72
	v_max3_f32 v226, v226, v73, v74
	v_max3_f32 v226, v226, v75, v76
	v_max3_f32 v226, v226, v77, v78
	v_max3_f32 v226, v226, v79, v80
	v_max3_f32 v226, v226, v81, v82
	v_max_f32_e32 v150, v226, v83
	v_mov_b32_e32 v151, v150
	s_waitcnt lgkmcnt(3)
	v_mfma_f32_32x32x16_bf16 v[52:67], v[218:221], v[88:91], v[52:67]
	v_permlane32_swap_b32_e32 v150, v151
	s_waitcnt lgkmcnt(2)
	v_mfma_f32_32x32x16_bf16 v[52:67], v[222:225], v[84:87], v[52:67]
	v_max_f32_e32 v150, v150, v151
	v_cmp_lt_f32_e32 vcc, s70, v150
	s_cbranch_vccnz .LBB0_1204
.LBB0_1195:
	v_exp_f32_e32 v151, v68
	v_exp_f32_e32 v159, v69
	v_exp_f32_e32 v165, v70
	v_exp_f32_e32 v167, v71
	v_exp_f32_e32 v169, v72
	v_exp_f32_e32 v171, v73
	v_exp_f32_e32 v173, v74
	v_exp_f32_e32 v175, v75
	v_cvt_pk_bf16_f32 v68, v151, v159
	v_cvt_pk_bf16_f32 v69, v165, v167
	v_cvt_pk_bf16_f32 v70, v169, v171
	v_cvt_pk_bf16_f32 v71, v173, v175
	v_exp_f32_e32 v158, v82
	v_exp_f32_e32 v150, v83
	v_max_f32_e32 v82, v53, v53
	v_max_f32_e32 v83, v52, v52
	s_waitcnt lgkmcnt(1)
	v_mfma_f32_32x32x16_bf16 v[20:35], v[136:139], v[68:71], v[20:35]
	v_exp_f32_e32 v168, v76
	v_exp_f32_e32 v170, v77
	v_exp_f32_e32 v172, v78
	v_exp_f32_e32 v174, v79
	v_max_f32_e32 v82, v83, v82
	v_exp_f32_e32 v164, v80
	v_exp_f32_e32 v166, v81
	s_waitcnt lgkmcnt(0)
	v_mfma_f32_32x32x16_bf16 v[4:19], v[132:135], v[68:71], v[4:19]
	v_max3_f32 v82, v82, v54, v55
	v_max3_f32 v82, v82, v56, v57
	v_max3_f32 v82, v82, v58, v59
	ds_read_b128 v[132:135], v154 offset:26656
	ds_read_b128 v[72:75], v154 offset:26688
	ds_read_b128 v[136:139], v154 offset:31264
	ds_read_b128 v[68:71], v154 offset:31296
	v_pk_add_f32 v[76:77], v[170:171], v[168:169]
	v_pk_add_f32 v[78:79], v[174:175], v[172:173]
	v_max3_f32 v82, v82, v60, v61
	v_pk_add_f32 v[76:77], v[78:79], v[76:77]
	v_pk_add_f32 v[78:79], v[166:167], v[164:165]
	v_pk_add_f32 v[80:81], v[158:159], v[150:151]
	v_max3_f32 v82, v82, v62, v63
	v_pk_add_f32 v[78:79], v[78:79], v[80:81]
	v_max3_f32 v82, v82, v64, v65
	v_pk_add_f32 v[80:81], v[76:77], v[78:79]
	v_cvt_pk_bf16_f32 v76, v168, v170
	v_cvt_pk_bf16_f32 v77, v172, v174
	v_cvt_pk_bf16_f32 v78, v164, v166
	v_cvt_pk_bf16_f32 v79, v158, v150
	v_max3_f32 v82, v82, v66, v67
	v_mov_b32_e32 v83, v82
	s_waitcnt lgkmcnt(3)
	v_mfma_f32_32x32x16_bf16 v[20:35], v[132:135], v[76:79], v[20:35]
	v_add_f32_e32 v81, 0, v81
	v_add_f32_e32 v80, v80, v81
	v_permlane32_swap_b32_e32 v82, v83
	s_waitcnt lgkmcnt(1)
	v_mfma_f32_32x32x16_bf16 v[4:19], v[136:139], v[76:79], v[4:19]
	s_waitcnt lgkmcnt(0)
	v_max_f32_e32 v77, v82, v83
	v_add_f32_e32 v76, v162, v80
	v_cmp_lt_f32_e32 vcc, s70, v77
	s_cbranch_vccnz .LBB0_1205
